# M_FINAL epilogue h-load hoist; FoX prompt loop: bias load no longer waited immediately (vmcnt(0) stall removed)
# speedup vs baseline: 1.0354x; 1.0055x over previous
.LBB0_69:
	s_add_i32 s80, s91, s92
	s_add_i32 s8, s80, 1
	s_cmp_lt_i32 s8, s88
	s_cselect_b64 s[78:79], -1, 0
	s_cmp_ge_i32 s8, s88
	s_cbranch_scc1 .LBB0_73
	v_add_u32_e32 v66, s76, v172
	v_mad_i64_i32 v[66:67], s[8:9], v66, s89, v[174:175]
	s_ashr_i32 s77, s76, 31
	v_lshl_add_u64 v[68:69], s[76:77], 1, v[176:177]
	global_load_dwordx4 v[162:165], v[66:67], off
	global_load_dwordx4 v[166:169], v[68:69], off
	s_and_saveexec_b64 s[8:9], s[10:11]
	s_cbranch_execz .LBB0_72
	v_add_u32_e32 v66, s76, v1
	v_ashrrev_i32_e32 v67, 31, v66
	v_lshl_add_u64 v[66:67], v[66:67], 2, s[2:3]
	global_load_dword v179, v[66:67], off

.LBB0_79:
	s_or_b64 exec, exec, s[80:81]
	s_andn2_b64 vcc, exec, s[78:79]
	s_cbranch_vccnz .LBB0_68
	s_xor_b32 s77, s8, 1
	s_mul_i32 s8, s77, 0x2400
	v_add_u32_e32 v66, s8, v180
	s_waitcnt vmcnt(1)
	ds_write_b128 v66, v[162:165]
	v_add_u32_e32 v66, s8, v181
	v_add_u32_e32 v66, 0x4800, v66
	s_waitcnt vmcnt(0)
	ds_write2_b64 v66, v[166:167], v[168:169] offset1:2
	s_and_saveexec_b64 s[8:9], s[10:11]
	s_cbranch_execz .LBB0_67
	v_lshl_add_u32 v66, s77, 8, v182
	v_mul_f32_e32 v179, 0xbfb8aa3b, v179
	ds_write_b32 v66, v179 offset:36864
	s_branch .LBB0_67

.LBB0_253:
	s_add_i32 s49, s4, 2
	s_add_u32 s16, s0, 0x80
	s_addc_u32 s5, s1, 0
	s_add_i32 s65, 0, 0x10000
	v_add_u32_e32 v142, s65, v145
	ds_read_b128 v[148:151], v142
	ds_read_b128 v[152:155], v142 offset:1024
	ds_read_b128 v[156:159], v142 offset:2048
	ds_read_b128 v[160:163], v142 offset:3072
	s_cmp_eq_u32 s41, s4
	s_cselect_b32 s4, s10, s16
	s_cselect_b32 s5, s11, s5
	s_cselect_b32 s17, s13, s48
	s_cselect_b32 s16, s12, s47
	v_lshl_add_u64 v[142:143], s[0:1], 0, v[138:139]
	s_add_i32 m0, s26, 0xc000
	ds_read_b128 v[164:167], v146
	ds_read_b128 v[168:171], v146 offset:1024
	ds_read_b128 v[172:175], v146 offset:2048
	ds_read_b128 v[176:179], v146 offset:3072
	ds_read_b128 v[180:183], v146 offset:4096
	ds_read_b128 v[204:207], v146 offset:5120
	ds_read_b128 v[208:211], v146 offset:6144
	ds_read_b128 v[212:215], v146 offset:7168
	global_load_lds_dwordx4 v[142:143], off
	v_lshl_add_u64 v[142:143], s[0:1], 0, v[140:141]
	s_add_i32 m0, s26, 0xe000
	s_nop 0
	global_load_lds_dwordx4 v[142:143], off
	s_waitcnt lgkmcnt(8)
	s_barrier
	s_waitcnt lgkmcnt(0)
	s_setprio 1
	s_waitcnt lgkmcnt(0)
	v_mfma_f32_16x16x32_bf16 v[126:129], v[148:151], v[164:167], v[126:129]
	v_mfma_f32_16x16x32_bf16 v[122:125], v[156:159], v[164:167], v[122:125]
	v_mfma_f32_16x16x32_bf16 v[110:113], v[148:151], v[172:175], v[110:113]
	v_mfma_f32_16x16x32_bf16 v[106:109], v[156:159], v[172:175], v[106:109]
	v_mfma_f32_16x16x32_bf16 v[94:97], v[148:151], v[180:183], v[94:97]
	v_mfma_f32_16x16x32_bf16 v[90:93], v[156:159], v[180:183], v[90:93]
	v_mfma_f32_16x16x32_bf16 v[78:81], v[148:151], v[208:211], v[78:81]
	v_mfma_f32_16x16x32_bf16 v[74:77], v[156:159], v[208:211], v[74:77]
	v_mfma_f32_16x16x32_bf16 v[126:129], v[152:155], v[168:171], v[126:129]
	v_mfma_f32_16x16x32_bf16 v[122:125], v[160:163], v[168:171], v[122:125]
	v_mfma_f32_16x16x32_bf16 v[110:113], v[152:155], v[176:179], v[110:113]
	v_mfma_f32_16x16x32_bf16 v[106:109], v[160:163], v[176:179], v[106:109]
	v_mfma_f32_16x16x32_bf16 v[94:97], v[152:155], v[204:207], v[94:97]
	v_mfma_f32_16x16x32_bf16 v[90:93], v[160:163], v[204:207], v[90:93]
	v_mfma_f32_16x16x32_bf16 v[78:81], v[152:155], v[212:215], v[78:81]
	v_mfma_f32_16x16x32_bf16 v[74:77], v[160:163], v[212:215], v[74:77]
	s_setprio 0
	s_barrier
	s_add_i32 s66, 0, 0x14000
	v_add_u32_e32 v142, s66, v145
	s_add_i32 s65, s65, s24
	ds_read_b128 v[216:219], v142
	ds_read_b128 v[220:223], v142 offset:1024
	ds_read_b128 v[224:227], v142 offset:2048
	ds_read_b128 v[228:231], v142 offset:3072
	v_lshl_add_u64 v[142:143], s[16:17], 0, v[132:133]
	s_mov_b32 m0, s65
	v_lshl_add_u64 v[184:185], s[16:17], 0, v[136:137]
	global_load_lds_dwordx4 v[142:143], off
	s_add_i32 m0, s65, 0x2000
	s_nop 0
	global_load_lds_dwordx4 v[184:185], off
	s_barrier
	s_waitcnt lgkmcnt(0)
	s_setprio 1
	s_waitcnt lgkmcnt(0)
	v_mfma_f32_16x16x32_bf16 v[114:117], v[216:219], v[164:167], v[114:117]
	v_mfma_f32_16x16x32_bf16 v[118:121], v[224:227], v[164:167], v[118:121]
	v_mfma_f32_16x16x32_bf16 v[98:101], v[216:219], v[172:175], v[98:101]
	v_mfma_f32_16x16x32_bf16 v[102:105], v[224:227], v[172:175], v[102:105]
	v_mfma_f32_16x16x32_bf16 v[82:85], v[216:219], v[180:183], v[82:85]
	v_mfma_f32_16x16x32_bf16 v[86:89], v[224:227], v[180:183], v[86:89]
	v_mfma_f32_16x16x32_bf16 v[66:69], v[216:219], v[208:211], v[66:69]
	v_mfma_f32_16x16x32_bf16 v[70:73], v[224:227], v[208:211], v[70:73]
	v_mfma_f32_16x16x32_bf16 v[114:117], v[220:223], v[168:171], v[114:117]
	v_mfma_f32_16x16x32_bf16 v[118:121], v[228:231], v[168:171], v[118:121]
	v_mfma_f32_16x16x32_bf16 v[98:101], v[220:223], v[176:179], v[98:101]
	v_mfma_f32_16x16x32_bf16 v[102:105], v[228:231], v[176:179], v[102:105]
	v_mfma_f32_16x16x32_bf16 v[82:85], v[220:223], v[204:207], v[82:85]
	v_mfma_f32_16x16x32_bf16 v[86:89], v[228:231], v[204:207], v[86:89]
	v_mfma_f32_16x16x32_bf16 v[66:69], v[220:223], v[212:215], v[66:69]
	v_mfma_f32_16x16x32_bf16 v[70:73], v[228:231], v[212:215], v[70:73]
	s_setprio 0
	s_mov_b32 m0, s26
	v_lshl_add_u64 v[232:233], s[4:5], 0, v[130:131]
	s_barrier
	ds_read_b128 v[164:167], v146 offset:16384
	ds_read_b128 v[168:171], v146 offset:17408
	ds_read_b128 v[172:175], v146 offset:18432
	ds_read_b128 v[176:179], v146 offset:19456
	ds_read_b128 v[180:183], v146 offset:20480
	ds_read_b128 v[204:207], v146 offset:21504
	ds_read_b128 v[208:211], v146 offset:22528
	ds_read_b128 v[212:215], v146 offset:23552
	global_load_lds_dwordx4 v[232:233], off
	v_lshl_add_u64 v[234:235], s[4:5], 0, v[134:135]
	s_mov_b32 m0, s27
	s_nop 0
	global_load_lds_dwordx4 v[234:235], off
	s_barrier
	s_waitcnt lgkmcnt(0)
	s_setprio 1
	s_waitcnt lgkmcnt(0)
	v_mfma_f32_16x16x32_bf16 v[62:65], v[148:151], v[164:167], v[62:65]
	v_mfma_f32_16x16x32_bf16 v[58:61], v[156:159], v[164:167], v[58:61]
	v_mfma_f32_16x16x32_bf16 v[46:49], v[148:151], v[172:175], v[46:49]
	v_mfma_f32_16x16x32_bf16 v[42:45], v[156:159], v[172:175], v[42:45]
	v_mfma_f32_16x16x32_bf16 v[30:33], v[148:151], v[180:183], v[30:33]
	v_mfma_f32_16x16x32_bf16 v[26:29], v[156:159], v[180:183], v[26:29]
	v_mfma_f32_16x16x32_bf16 v[14:17], v[148:151], v[208:211], v[14:17]
	v_mfma_f32_16x16x32_bf16 v[10:13], v[156:159], v[208:211], v[10:13]
	v_mfma_f32_16x16x32_bf16 v[62:65], v[152:155], v[168:171], v[62:65]
	v_mfma_f32_16x16x32_bf16 v[58:61], v[160:163], v[168:171], v[58:61]
	v_mfma_f32_16x16x32_bf16 v[46:49], v[152:155], v[176:179], v[46:49]
	v_mfma_f32_16x16x32_bf16 v[42:45], v[160:163], v[176:179], v[42:45]
	v_mfma_f32_16x16x32_bf16 v[30:33], v[152:155], v[204:207], v[30:33]
	v_mfma_f32_16x16x32_bf16 v[26:29], v[160:163], v[204:207], v[26:29]
	v_mfma_f32_16x16x32_bf16 v[14:17], v[152:155], v[212:215], v[14:17]
	v_mfma_f32_16x16x32_bf16 v[10:13], v[160:163], v[212:215], v[10:13]
	s_setprio 0
	s_barrier
	s_add_u32 s16, s16, s92
	s_addc_u32 s17, s17, 0
	s_add_i32 s65, s66, s24
	v_lshl_add_u64 v[236:237], s[16:17], 0, v[132:133]
	s_mov_b32 m0, s65
	v_lshl_add_u64 v[238:239], s[16:17], 0, v[136:137]
	global_load_lds_dwordx4 v[236:237], off
	s_add_i32 m0, s65, 0x2000
	s_nop 0
	global_load_lds_dwordx4 v[238:239], off
	s_waitcnt vmcnt(6)
	s_barrier
	s_setprio 1
	v_mfma_f32_16x16x32_bf16 v[50:53], v[216:219], v[164:167], v[50:53]
	v_mfma_f32_16x16x32_bf16 v[54:57], v[224:227], v[164:167], v[54:57]
	v_mfma_f32_16x16x32_bf16 v[34:37], v[216:219], v[172:175], v[34:37]
	v_mfma_f32_16x16x32_bf16 v[38:41], v[224:227], v[172:175], v[38:41]
	v_mfma_f32_16x16x32_bf16 v[18:21], v[216:219], v[180:183], v[18:21]
	v_mfma_f32_16x16x32_bf16 v[22:25], v[224:227], v[180:183], v[22:25]
	v_mfma_f32_16x16x32_bf16 v[6:9], v[216:219], v[208:211], v[6:9]
	v_mfma_f32_16x16x32_bf16 v[2:5], v[224:227], v[208:211], v[2:5]
	v_mfma_f32_16x16x32_bf16 v[50:53], v[220:223], v[168:171], v[50:53]
	v_mfma_f32_16x16x32_bf16 v[54:57], v[228:231], v[168:171], v[54:57]
	v_mfma_f32_16x16x32_bf16 v[34:37], v[220:223], v[176:179], v[34:37]
	v_mfma_f32_16x16x32_bf16 v[38:41], v[228:231], v[176:179], v[38:41]
	v_mfma_f32_16x16x32_bf16 v[18:21], v[220:223], v[204:207], v[18:21]
	v_mfma_f32_16x16x32_bf16 v[22:25], v[228:231], v[204:207], v[22:25]
	v_mfma_f32_16x16x32_bf16 v[6:9], v[220:223], v[212:215], v[6:9]
	v_mfma_f32_16x16x32_bf16 v[2:5], v[228:231], v[212:215], v[2:5]
	s_setprio 0
	s_add_i32 s16, 0, 0x18000
	v_add_u32_e32 v147, s16, v145
	s_barrier
	ds_read_b128 v[148:151], v147
	ds_read_b128 v[152:155], v147 offset:1024
	ds_read_b128 v[156:159], v147 offset:2048
	ds_read_b128 v[160:163], v147 offset:3072
	s_add_u32 s4, s4, s92
	s_addc_u32 s5, s5, 0
	s_mov_b32 m0, s28
	v_lshl_add_u64 v[216:217], s[4:5], 0, v[130:131]
	ds_read_b128 v[164:167], v146 offset:32768
	ds_read_b128 v[168:171], v146 offset:33792
	ds_read_b128 v[172:175], v146 offset:34816
	ds_read_b128 v[176:179], v146 offset:35840
	ds_read_b128 v[180:183], v146 offset:36864
	ds_read_b128 v[204:207], v146 offset:37888
	ds_read_b128 v[208:211], v146 offset:38912
	ds_read_b128 v[212:215], v146 offset:39936
	global_load_lds_dwordx4 v[216:217], off
	v_lshl_add_u64 v[216:217], s[4:5], 0, v[134:135]
	s_mov_b32 m0, s29
	s_nop 0
	global_load_lds_dwordx4 v[216:217], off
	s_waitcnt lgkmcnt(8)
	s_barrier
	s_waitcnt lgkmcnt(0)
	s_setprio 1
	s_waitcnt lgkmcnt(0)
	v_mfma_f32_16x16x32_bf16 v[126:129], v[148:151], v[164:167], v[126:129]
	v_mfma_f32_16x16x32_bf16 v[122:125], v[156:159], v[164:167], v[122:125]
	v_mfma_f32_16x16x32_bf16 v[110:113], v[148:151], v[172:175], v[110:113]
	v_mfma_f32_16x16x32_bf16 v[106:109], v[156:159], v[172:175], v[106:109]
	v_mfma_f32_16x16x32_bf16 v[94:97], v[148:151], v[180:183], v[94:97]
	v_mfma_f32_16x16x32_bf16 v[90:93], v[156:159], v[180:183], v[90:93]
	v_mfma_f32_16x16x32_bf16 v[78:81], v[148:151], v[208:211], v[78:81]
	v_mfma_f32_16x16x32_bf16 v[74:77], v[156:159], v[208:211], v[74:77]
	v_mfma_f32_16x16x32_bf16 v[126:129], v[152:155], v[168:171], v[126:129]
	v_mfma_f32_16x16x32_bf16 v[122:125], v[160:163], v[168:171], v[122:125]
	v_mfma_f32_16x16x32_bf16 v[110:113], v[152:155], v[176:179], v[110:113]
	v_mfma_f32_16x16x32_bf16 v[106:109], v[160:163], v[176:179], v[106:109]
	v_mfma_f32_16x16x32_bf16 v[94:97], v[152:155], v[204:207], v[94:97]
	v_mfma_f32_16x16x32_bf16 v[90:93], v[160:163], v[204:207], v[90:93]
	v_mfma_f32_16x16x32_bf16 v[78:81], v[152:155], v[212:215], v[78:81]
	v_mfma_f32_16x16x32_bf16 v[74:77], v[160:163], v[212:215], v[74:77]
	s_setprio 0
	s_barrier
	s_add_i32 s4, 0, 0x1c000
	s_add_i32 s5, s16, s24
	v_add_u32_e32 v147, s4, v145
	v_lshl_add_u64 v[142:143], v[142:143], 0, s[6:7]
	s_mov_b32 m0, s5
	ds_read_b128 v[216:219], v147
	ds_read_b128 v[220:223], v147 offset:1024
	ds_read_b128 v[224:227], v147 offset:2048
	ds_read_b128 v[228:231], v147 offset:3072
	global_load_lds_dwordx4 v[142:143], off
	v_lshl_add_u64 v[142:143], v[184:185], 0, s[6:7]
	s_add_i32 m0, s5, 0x2000
	s_nop 0
	global_load_lds_dwordx4 v[142:143], off
	s_barrier
	s_waitcnt lgkmcnt(0)
	s_setprio 1
	s_waitcnt lgkmcnt(0)
	v_mfma_f32_16x16x32_bf16 v[114:117], v[216:219], v[164:167], v[114:117]
	v_mfma_f32_16x16x32_bf16 v[118:121], v[224:227], v[164:167], v[118:121]
	v_mfma_f32_16x16x32_bf16 v[98:101], v[216:219], v[172:175], v[98:101]
	v_mfma_f32_16x16x32_bf16 v[102:105], v[224:227], v[172:175], v[102:105]
	v_mfma_f32_16x16x32_bf16 v[82:85], v[216:219], v[180:183], v[82:85]
	v_mfma_f32_16x16x32_bf16 v[86:89], v[224:227], v[180:183], v[86:89]
	v_mfma_f32_16x16x32_bf16 v[66:69], v[216:219], v[208:211], v[66:69]
	v_mfma_f32_16x16x32_bf16 v[70:73], v[224:227], v[208:211], v[70:73]
	v_mfma_f32_16x16x32_bf16 v[114:117], v[220:223], v[168:171], v[114:117]
	v_mfma_f32_16x16x32_bf16 v[118:121], v[228:231], v[168:171], v[118:121]
	v_mfma_f32_16x16x32_bf16 v[98:101], v[220:223], v[176:179], v[98:101]
	v_mfma_f32_16x16x32_bf16 v[102:105], v[228:231], v[176:179], v[102:105]
	v_mfma_f32_16x16x32_bf16 v[82:85], v[220:223], v[204:207], v[82:85]
	v_mfma_f32_16x16x32_bf16 v[86:89], v[228:231], v[204:207], v[86:89]
	v_mfma_f32_16x16x32_bf16 v[66:69], v[220:223], v[212:215], v[66:69]
	v_mfma_f32_16x16x32_bf16 v[70:73], v[228:231], v[212:215], v[70:73]
	s_setprio 0
	s_mov_b32 m0, s35
	v_lshl_add_u64 v[142:143], v[232:233], 0, s[6:7]
	s_barrier
	ds_read_b128 v[164:167], v146 offset:49152
	ds_read_b128 v[168:171], v146 offset:50176
	ds_read_b128 v[172:175], v146 offset:51200
	ds_read_b128 v[176:179], v146 offset:52224
	ds_read_b128 v[180:183], v146 offset:53248
	ds_read_b128 v[204:207], v146 offset:54272
	ds_read_b128 v[208:211], v146 offset:55296
	ds_read_b128 v[212:215], v146 offset:56320
	global_load_lds_dwordx4 v[142:143], off
	v_lshl_add_u64 v[142:143], v[234:235], 0, s[6:7]
	s_mov_b32 m0, s40
	s_nop 0
	global_load_lds_dwordx4 v[142:143], off
	s_barrier
	s_waitcnt lgkmcnt(0)
	s_setprio 1
	s_waitcnt lgkmcnt(0)
	v_mfma_f32_16x16x32_bf16 v[62:65], v[148:151], v[164:167], v[62:65]
	v_mfma_f32_16x16x32_bf16 v[58:61], v[156:159], v[164:167], v[58:61]
	v_mfma_f32_16x16x32_bf16 v[46:49], v[148:151], v[172:175], v[46:49]
	v_mfma_f32_16x16x32_bf16 v[42:45], v[156:159], v[172:175], v[42:45]
	v_mfma_f32_16x16x32_bf16 v[30:33], v[148:151], v[180:183], v[30:33]
	v_mfma_f32_16x16x32_bf16 v[26:29], v[156:159], v[180:183], v[26:29]
	v_mfma_f32_16x16x32_bf16 v[14:17], v[148:151], v[208:211], v[14:17]
	v_mfma_f32_16x16x32_bf16 v[10:13], v[156:159], v[208:211], v[10:13]
	v_mfma_f32_16x16x32_bf16 v[62:65], v[152:155], v[168:171], v[62:65]
	v_mfma_f32_16x16x32_bf16 v[58:61], v[160:163], v[168:171], v[58:61]
	v_mfma_f32_16x16x32_bf16 v[46:49], v[152:155], v[176:179], v[46:49]
	v_mfma_f32_16x16x32_bf16 v[42:45], v[160:163], v[176:179], v[42:45]
	v_mfma_f32_16x16x32_bf16 v[30:33], v[152:155], v[204:207], v[30:33]
	v_mfma_f32_16x16x32_bf16 v[26:29], v[160:163], v[204:207], v[26:29]
	v_mfma_f32_16x16x32_bf16 v[14:17], v[152:155], v[212:215], v[14:17]
	v_mfma_f32_16x16x32_bf16 v[10:13], v[160:163], v[212:215], v[10:13]
	s_setprio 0
	s_barrier
	s_add_i32 s4, s4, s24
	v_lshl_add_u64 v[142:143], v[236:237], 0, s[6:7]
	s_mov_b32 m0, s4
	s_nop 0
	global_load_lds_dwordx4 v[142:143], off
	v_lshl_add_u64 v[142:143], v[238:239], 0, s[6:7]
	s_add_i32 m0, s4, 0x2000
	s_nop 0
	global_load_lds_dwordx4 v[142:143], off
	s_waitcnt vmcnt(6)
	s_barrier
	s_setprio 1
	v_mfma_f32_16x16x32_bf16 v[50:53], v[216:219], v[164:167], v[50:53]
	v_mfma_f32_16x16x32_bf16 v[54:57], v[224:227], v[164:167], v[54:57]
	v_mfma_f32_16x16x32_bf16 v[34:37], v[216:219], v[172:175], v[34:37]
	v_mfma_f32_16x16x32_bf16 v[38:41], v[224:227], v[172:175], v[38:41]
	v_mfma_f32_16x16x32_bf16 v[18:21], v[216:219], v[180:183], v[18:21]
	v_mfma_f32_16x16x32_bf16 v[22:25], v[224:227], v[180:183], v[22:25]
	v_mfma_f32_16x16x32_bf16 v[6:9], v[216:219], v[208:211], v[6:9]
	v_mfma_f32_16x16x32_bf16 v[2:5], v[224:227], v[208:211], v[2:5]
	v_mfma_f32_16x16x32_bf16 v[50:53], v[220:223], v[168:171], v[50:53]
	v_mfma_f32_16x16x32_bf16 v[54:57], v[228:231], v[168:171], v[54:57]
	v_mfma_f32_16x16x32_bf16 v[34:37], v[220:223], v[176:179], v[34:37]
	v_mfma_f32_16x16x32_bf16 v[38:41], v[228:231], v[176:179], v[38:41]
	v_mfma_f32_16x16x32_bf16 v[18:21], v[220:223], v[204:207], v[18:21]
	v_mfma_f32_16x16x32_bf16 v[22:25], v[228:231], v[204:207], v[22:25]
	v_mfma_f32_16x16x32_bf16 v[6:9], v[220:223], v[212:215], v[6:9]
	v_mfma_f32_16x16x32_bf16 v[2:5], v[228:231], v[212:215], v[2:5]
	s_setprio 0
	s_add_u32 s0, s0, 0x100
	s_addc_u32 s1, s1, 0
	s_add_u32 s47, s47, 0x100
	s_addc_u32 s48, s48, 0
	s_cmp_ge_u32 s49, s30
	s_mov_b32 s4, s49
	s_barrier
	s_cbranch_scc0 .LBB0_253
	s_lshl_b32 s0, s45, 8
	v_mov_b32_e32 v142, v144
	v_mov_b32_e32 v143, v1
	s_add_i32 s0, s0, s31
	v_readlane_b32 s4, v242, 7
	v_add_u32_e32 v147, s0, v142
	s_lshl_b32 s0, s46, 8
	s_or_b32 s0, s0, s34
	v_add_u32_e32 v154, s50, v147
	v_lshl_add_u32 v152, v143, 3, s0
	v_ashrrev_i32_e32 v155, 31, v154
	v_add_u32_e32 v142, 0xffff0000, v154
	v_mov_b32_e32 v143, v0
	v_readlane_b32 s0, v243, 48
	v_ashrrev_i32_e32 v153, 31, v152
	v_lshlrev_b64 v[156:157], 12, v[142:143]
	v_lshlrev_b64 v[142:143], 11, v[154:155]
	v_readlane_b32 s1, v243, 49
	s_mov_b32 s16, 0x10000
	v_readlane_b32 s5, v242, 8
	v_lshl_add_u64 v[148:149], s[0:1], 0, v[142:143]
	v_lshlrev_b64 v[142:143], 1, v[152:153]
	v_lshl_add_u64 v[158:159], v[148:149], 0, v[142:143]
	v_lshlrev_b32_e32 v160, 11, v144
	v_lshl_add_u32 v160, v152, 1, v160
	s_lshl_b32 s65, s45, 8
	s_add_i32 s65, s65, s31
	s_add_i32 s48, s65, s50
	s_lshl_b32 s48, s48, 11
	s_add_u32 s48, s0, s48
	s_addc_u32 s49, s1, 0
	global_load_dwordx4 v[148:151], v160, s[48:49]
	global_load_dwordx4 v[162:165], v160, s[48:49] offset:256
	s_add_i32 s48, s65, s83
	s_lshl_b32 s48, s48, 11
	s_add_u32 s48, s0, s48
	s_addc_u32 s49, s1, 0
	global_load_dwordx4 v[166:169], v160, s[48:49]
	global_load_dwordx4 v[170:173], v160, s[48:49] offset:256
	s_add_i32 s48, s65, s91
	s_lshl_b32 s48, s48, 11
	s_add_u32 s48, s0, s48
	s_addc_u32 s49, s1, 0
	global_load_dwordx4 v[174:177], v160, s[48:49]
	global_load_dwordx4 v[178:181], v160, s[48:49] offset:256
	s_add_i32 s48, s65, s51
	s_lshl_b32 s48, s48, 11
	s_add_u32 s48, s0, s48
	s_addc_u32 s49, s1, 0
	global_load_dwordx4 v[182:185], v160, s[48:49]
	global_load_dwordx4 v[204:207], v160, s[48:49] offset:256
	s_add_i32 s48, s65, s88
	s_lshl_b32 s48, s48, 11
	s_add_u32 s48, s0, s48
	s_addc_u32 s49, s1, 0
	global_load_dwordx4 v[208:211], v160, s[48:49]
	global_load_dwordx4 v[212:215], v160, s[48:49] offset:256
	s_add_i32 s48, s65, s60
	s_lshl_b32 s48, s48, 11
	s_add_u32 s48, s0, s48
	s_addc_u32 s49, s1, 0
	global_load_dwordx4 v[216:219], v160, s[48:49]
	global_load_dwordx4 v[220:223], v160, s[48:49] offset:256
	s_add_i32 s48, s65, s61
	s_lshl_b32 s48, s48, 11
	s_add_u32 s48, s0, s48
	s_addc_u32 s49, s1, 0
	global_load_dwordx4 v[224:227], v160, s[48:49]
	global_load_dwordx4 v[228:231], v160, s[48:49] offset:256
	s_add_i32 s48, s65, s62
	s_lshl_b32 s48, s48, 11
	s_add_u32 s48, s0, s48
	s_addc_u32 s49, s1, 0
	global_load_dwordx4 v[232:235], v160, s[48:49]
	global_load_dwordx4 v[236:239], v160, s[48:49] offset:256
	v_cmp_gt_i32_e32 vcc, s16, v154
	s_mov_b32 s45, s44
	s_mov_b32 s46, s43
	s_waitcnt vmcnt(15)
	v_lshlrev_b32_e32 v160, 16, v148
	v_and_b32_e32 v161, 0xffff0000, v148
	v_lshlrev_b32_e32 v148, 16, v149
	v_and_b32_e32 v149, 0xffff0000, v149
	v_pk_add_f32 v[128:129], v[128:129], v[148:149]
	v_lshlrev_b32_e32 v148, 16, v150
	v_and_b32_e32 v149, 0xffff0000, v150
	v_pk_add_f32 v[148:149], v[122:123], v[148:149]
	v_lshlrev_b32_e32 v122, 16, v151
	v_and_b32_e32 v123, 0xffff0000, v151
	v_pk_add_f32 v[150:151], v[124:125], v[122:123]
	v_lshlrev_b64 v[122:123], 12, v[154:155]
	v_lshl_add_u64 v[122:123], s[74:75], 0, v[122:123]
	v_lshl_add_u64 v[124:125], s[4:5], 0, v[156:157]
	v_cndmask_b32_e32 v125, v125, v123, vcc
	v_cndmask_b32_e32 v124, v124, v122, vcc
	v_lshlrev_b64 v[122:123], 2, v[152:153]
	v_pk_add_f32 v[126:127], v[126:127], v[160:161]
	v_lshl_add_u64 v[152:153], v[124:125], 0, v[122:123]
	global_store_dwordx4 v[152:153], v[126:129], off nt
	global_store_dwordx4 v[152:153], v[148:151], off offset:16 nt
	s_waitcnt vmcnt(16)
	v_lshlrev_b32_e32 v128, 16, v165
	v_and_b32_e32 v129, 0xffff0000, v165
	v_pk_add_f32 v[120:121], v[120:121], v[128:129]
	v_lshlrev_b32_e32 v128, 16, v164
	v_and_b32_e32 v129, 0xffff0000, v164
	v_lshlrev_b32_e32 v126, 16, v163
	v_and_b32_e32 v127, 0xffff0000, v163
	v_pk_add_f32 v[116:117], v[116:117], v[126:127]
	v_lshlrev_b32_e32 v126, 16, v162
	v_and_b32_e32 v127, 0xffff0000, v162
	v_pk_add_f32 v[118:119], v[118:119], v[128:129]
	v_pk_add_f32 v[114:115], v[114:115], v[126:127]
	global_store_dwordx4 v[152:153], v[114:117], off offset:512 nt
	global_store_dwordx4 v[152:153], v[118:121], off offset:528 nt
	s_nop 0
	v_mov_b32_e32 v115, v0
	v_add_u32_e32 v118, s83, v147
	v_ashrrev_i32_e32 v119, 31, v118
	v_add_u32_e32 v114, 0xffff0000, v118
	v_lshlrev_b64 v[120:121], 12, v[114:115]
	v_lshlrev_b64 v[114:115], 11, v[118:119]
	v_lshl_add_u64 v[114:115], s[0:1], 0, v[114:115]
	v_lshl_add_u64 v[124:125], v[114:115], 0, v[142:143]
	v_cmp_gt_i32_e32 vcc, s16, v118
	s_waitcnt vmcnt(17)
	v_lshlrev_b32_e32 v126, 16, v166
	v_and_b32_e32 v127, 0xffff0000, v166
	v_lshlrev_b32_e32 v114, 16, v167
	v_and_b32_e32 v115, 0xffff0000, v167
	v_pk_add_f32 v[112:113], v[112:113], v[114:115]
	v_lshlrev_b32_e32 v114, 16, v168
	v_and_b32_e32 v115, 0xffff0000, v168
	v_pk_add_f32 v[106:107], v[106:107], v[114:115]
	v_lshlrev_b32_e32 v114, 16, v169
	v_and_b32_e32 v115, 0xffff0000, v169
	v_pk_add_f32 v[108:109], v[108:109], v[114:115]
	v_lshlrev_b64 v[114:115], 12, v[118:119]
	v_lshl_add_u64 v[114:115], s[74:75], 0, v[114:115]
	v_lshl_add_u64 v[116:117], s[4:5], 0, v[120:121]
	v_cndmask_b32_e32 v115, v117, v115, vcc
	v_cndmask_b32_e32 v114, v116, v114, vcc
	v_pk_add_f32 v[110:111], v[110:111], v[126:127]
	v_lshl_add_u64 v[114:115], v[114:115], 0, v[122:123]
	global_store_dwordx4 v[114:115], v[110:113], off nt
	global_store_dwordx4 v[114:115], v[106:109], off offset:16 nt
	s_waitcnt vmcnt(18)
	v_lshlrev_b32_e32 v110, 16, v173
	v_and_b32_e32 v111, 0xffff0000, v173
	v_pk_add_f32 v[104:105], v[104:105], v[110:111]
	v_lshlrev_b32_e32 v110, 16, v172
	v_and_b32_e32 v111, 0xffff0000, v172
	v_lshlrev_b32_e32 v108, 16, v171
	v_and_b32_e32 v109, 0xffff0000, v171
	v_pk_add_f32 v[100:101], v[100:101], v[108:109]
	v_lshlrev_b32_e32 v108, 16, v170
	v_and_b32_e32 v109, 0xffff0000, v170
	v_pk_add_f32 v[102:103], v[102:103], v[110:111]
	v_pk_add_f32 v[98:99], v[98:99], v[108:109]
	global_store_dwordx4 v[114:115], v[98:101], off offset:512 nt
	global_store_dwordx4 v[114:115], v[102:105], off offset:528 nt
	s_nop 0
	v_mov_b32_e32 v99, v0
	v_add_u32_e32 v102, s91, v147
	v_ashrrev_i32_e32 v103, 31, v102
	v_add_u32_e32 v98, 0xffff0000, v102
	v_lshlrev_b64 v[104:105], 12, v[98:99]
	v_lshlrev_b64 v[98:99], 11, v[102:103]
	v_lshl_add_u64 v[98:99], s[0:1], 0, v[98:99]
	v_lshl_add_u64 v[106:107], v[98:99], 0, v[142:143]
	v_cmp_gt_i32_e32 vcc, s16, v102
	s_waitcnt vmcnt(19)
	v_lshlrev_b32_e32 v108, 16, v174
	v_and_b32_e32 v109, 0xffff0000, v174
	v_lshlrev_b32_e32 v98, 16, v175
	v_and_b32_e32 v99, 0xffff0000, v175
	v_pk_add_f32 v[96:97], v[96:97], v[98:99]
	v_lshlrev_b32_e32 v98, 16, v176
	v_and_b32_e32 v99, 0xffff0000, v176
	v_pk_add_f32 v[90:91], v[90:91], v[98:99]
	v_lshlrev_b32_e32 v98, 16, v177
	v_and_b32_e32 v99, 0xffff0000, v177
	v_pk_add_f32 v[92:93], v[92:93], v[98:99]
	v_lshlrev_b64 v[98:99], 12, v[102:103]
	v_lshl_add_u64 v[98:99], s[74:75], 0, v[98:99]
	v_lshl_add_u64 v[100:101], s[4:5], 0, v[104:105]
	v_cndmask_b32_e32 v99, v101, v99, vcc
	v_cndmask_b32_e32 v98, v100, v98, vcc
	v_pk_add_f32 v[94:95], v[94:95], v[108:109]
	v_lshl_add_u64 v[98:99], v[98:99], 0, v[122:123]
	global_store_dwordx4 v[98:99], v[94:97], off nt
	global_store_dwordx4 v[98:99], v[90:93], off offset:16 nt
	s_waitcnt vmcnt(20)
	v_lshlrev_b32_e32 v94, 16, v181
	v_and_b32_e32 v95, 0xffff0000, v181
	v_pk_add_f32 v[88:89], v[88:89], v[94:95]
	v_lshlrev_b32_e32 v94, 16, v180
	v_and_b32_e32 v95, 0xffff0000, v180
	v_lshlrev_b32_e32 v92, 16, v179
	v_and_b32_e32 v93, 0xffff0000, v179
	v_pk_add_f32 v[84:85], v[84:85], v[92:93]
	v_lshlrev_b32_e32 v92, 16, v178
	v_and_b32_e32 v93, 0xffff0000, v178
	v_pk_add_f32 v[86:87], v[86:87], v[94:95]
	v_pk_add_f32 v[82:83], v[82:83], v[92:93]
	global_store_dwordx4 v[98:99], v[82:85], off offset:512 nt
	global_store_dwordx4 v[98:99], v[86:89], off offset:528 nt
	s_nop 0
	v_mov_b32_e32 v83, v0
	v_add_u32_e32 v86, s51, v147
	v_ashrrev_i32_e32 v87, 31, v86
	v_add_u32_e32 v82, 0xffff0000, v86
	v_lshlrev_b64 v[88:89], 12, v[82:83]
	v_lshlrev_b64 v[82:83], 11, v[86:87]
	v_lshl_add_u64 v[82:83], s[0:1], 0, v[82:83]
	v_lshl_add_u64 v[90:91], v[82:83], 0, v[142:143]
	v_cmp_gt_i32_e32 vcc, s16, v86
	s_waitcnt vmcnt(21)
	v_lshlrev_b32_e32 v92, 16, v182
	v_and_b32_e32 v93, 0xffff0000, v182
	v_lshlrev_b32_e32 v82, 16, v183
	v_and_b32_e32 v83, 0xffff0000, v183
	v_pk_add_f32 v[80:81], v[80:81], v[82:83]
	v_lshlrev_b32_e32 v82, 16, v184
	v_and_b32_e32 v83, 0xffff0000, v184
	v_pk_add_f32 v[74:75], v[74:75], v[82:83]
	v_lshlrev_b32_e32 v82, 16, v185
	v_and_b32_e32 v83, 0xffff0000, v185
	v_pk_add_f32 v[76:77], v[76:77], v[82:83]
	v_lshlrev_b64 v[82:83], 12, v[86:87]
	v_lshl_add_u64 v[82:83], s[74:75], 0, v[82:83]
	v_lshl_add_u64 v[84:85], s[4:5], 0, v[88:89]
	v_cndmask_b32_e32 v83, v85, v83, vcc
	v_cndmask_b32_e32 v82, v84, v82, vcc
	v_pk_add_f32 v[78:79], v[78:79], v[92:93]
	v_lshl_add_u64 v[82:83], v[82:83], 0, v[122:123]
	global_store_dwordx4 v[82:83], v[78:81], off nt
	global_store_dwordx4 v[82:83], v[74:77], off offset:16 nt
	s_waitcnt vmcnt(22)
	v_lshlrev_b32_e32 v78, 16, v207
	v_and_b32_e32 v79, 0xffff0000, v207
	v_pk_add_f32 v[72:73], v[72:73], v[78:79]
	v_lshlrev_b32_e32 v78, 16, v206
	v_and_b32_e32 v79, 0xffff0000, v206
	v_lshlrev_b32_e32 v76, 16, v205
	v_and_b32_e32 v77, 0xffff0000, v205
	v_pk_add_f32 v[68:69], v[68:69], v[76:77]
	v_lshlrev_b32_e32 v76, 16, v204
	v_and_b32_e32 v77, 0xffff0000, v204
	v_pk_add_f32 v[70:71], v[70:71], v[78:79]
	v_pk_add_f32 v[66:67], v[66:67], v[76:77]
	global_store_dwordx4 v[82:83], v[66:69], off offset:512 nt
	global_store_dwordx4 v[82:83], v[70:73], off offset:528 nt
	s_nop 0
	v_mov_b32_e32 v67, v0
	v_add_u32_e32 v70, s88, v147
	v_ashrrev_i32_e32 v71, 31, v70
	v_add_u32_e32 v66, 0xffff0000, v70
	v_lshlrev_b64 v[72:73], 12, v[66:67]
	v_lshlrev_b64 v[66:67], 11, v[70:71]
	v_lshl_add_u64 v[66:67], s[0:1], 0, v[66:67]
	v_lshl_add_u64 v[74:75], v[66:67], 0, v[142:143]
	v_cmp_gt_i32_e32 vcc, s16, v70
	s_waitcnt vmcnt(23)
	v_lshlrev_b32_e32 v76, 16, v208
	v_and_b32_e32 v77, 0xffff0000, v208
	v_lshlrev_b32_e32 v66, 16, v209
	v_and_b32_e32 v67, 0xffff0000, v209
	v_pk_add_f32 v[64:65], v[64:65], v[66:67]
	v_lshlrev_b32_e32 v66, 16, v210
	v_and_b32_e32 v67, 0xffff0000, v210
	v_pk_add_f32 v[58:59], v[58:59], v[66:67]
	v_lshlrev_b32_e32 v66, 16, v211
	v_and_b32_e32 v67, 0xffff0000, v211
	v_pk_add_f32 v[60:61], v[60:61], v[66:67]
	v_lshlrev_b64 v[66:67], 12, v[70:71]
	v_lshl_add_u64 v[66:67], s[74:75], 0, v[66:67]
	v_lshl_add_u64 v[68:69], s[4:5], 0, v[72:73]
	v_cndmask_b32_e32 v67, v69, v67, vcc
	v_cndmask_b32_e32 v66, v68, v66, vcc
	v_pk_add_f32 v[62:63], v[62:63], v[76:77]
	v_lshl_add_u64 v[66:67], v[66:67], 0, v[122:123]
	global_store_dwordx4 v[66:67], v[62:65], off nt
	global_store_dwordx4 v[66:67], v[58:61], off offset:16 nt
	s_waitcnt vmcnt(24)
	v_lshlrev_b32_e32 v62, 16, v215
	v_and_b32_e32 v63, 0xffff0000, v215
	v_pk_add_f32 v[56:57], v[56:57], v[62:63]
	v_lshlrev_b32_e32 v62, 16, v214
	v_and_b32_e32 v63, 0xffff0000, v214
	v_lshlrev_b32_e32 v60, 16, v213
	v_and_b32_e32 v61, 0xffff0000, v213
	v_pk_add_f32 v[52:53], v[52:53], v[60:61]
	v_lshlrev_b32_e32 v60, 16, v212
	v_and_b32_e32 v61, 0xffff0000, v212
	v_pk_add_f32 v[54:55], v[54:55], v[62:63]
	v_pk_add_f32 v[50:51], v[50:51], v[60:61]
	global_store_dwordx4 v[66:67], v[50:53], off offset:512 nt
	global_store_dwordx4 v[66:67], v[54:57], off offset:528 nt
	s_nop 0
	v_mov_b32_e32 v51, v0
	v_add_u32_e32 v54, s60, v147
	v_ashrrev_i32_e32 v55, 31, v54
	v_add_u32_e32 v50, 0xffff0000, v54
	v_lshlrev_b64 v[56:57], 12, v[50:51]
	v_lshlrev_b64 v[50:51], 11, v[54:55]
	v_lshl_add_u64 v[50:51], s[0:1], 0, v[50:51]
	v_lshl_add_u64 v[58:59], v[50:51], 0, v[142:143]
	v_cmp_gt_i32_e32 vcc, s16, v54
	s_waitcnt vmcnt(25)
	v_lshlrev_b32_e32 v60, 16, v216
	v_and_b32_e32 v61, 0xffff0000, v216
	v_lshlrev_b32_e32 v50, 16, v217
	v_and_b32_e32 v51, 0xffff0000, v217
	v_pk_add_f32 v[48:49], v[48:49], v[50:51]
	v_lshlrev_b32_e32 v50, 16, v218
	v_and_b32_e32 v51, 0xffff0000, v218
	v_pk_add_f32 v[42:43], v[42:43], v[50:51]
	v_lshlrev_b32_e32 v50, 16, v219
	v_and_b32_e32 v51, 0xffff0000, v219
	v_pk_add_f32 v[44:45], v[44:45], v[50:51]
	v_lshlrev_b64 v[50:51], 12, v[54:55]
	v_lshl_add_u64 v[50:51], s[74:75], 0, v[50:51]
	v_lshl_add_u64 v[52:53], s[4:5], 0, v[56:57]
	v_cndmask_b32_e32 v51, v53, v51, vcc
	v_cndmask_b32_e32 v50, v52, v50, vcc
	v_pk_add_f32 v[46:47], v[46:47], v[60:61]
	v_lshl_add_u64 v[50:51], v[50:51], 0, v[122:123]
	global_store_dwordx4 v[50:51], v[46:49], off nt
	global_store_dwordx4 v[50:51], v[42:45], off offset:16 nt
	s_waitcnt vmcnt(26)
	v_lshlrev_b32_e32 v46, 16, v223
	v_and_b32_e32 v47, 0xffff0000, v223
	v_pk_add_f32 v[40:41], v[40:41], v[46:47]
	v_lshlrev_b32_e32 v46, 16, v222
	v_and_b32_e32 v47, 0xffff0000, v222
	v_lshlrev_b32_e32 v44, 16, v221
	v_and_b32_e32 v45, 0xffff0000, v221
	v_pk_add_f32 v[36:37], v[36:37], v[44:45]
	v_lshlrev_b32_e32 v44, 16, v220
	v_and_b32_e32 v45, 0xffff0000, v220
	v_pk_add_f32 v[38:39], v[38:39], v[46:47]
	v_pk_add_f32 v[34:35], v[34:35], v[44:45]
	global_store_dwordx4 v[50:51], v[34:37], off offset:512 nt
	global_store_dwordx4 v[50:51], v[38:41], off offset:528 nt
	s_nop 0
	v_mov_b32_e32 v35, v0
	v_add_u32_e32 v38, s61, v147
	v_ashrrev_i32_e32 v39, 31, v38
	v_add_u32_e32 v34, 0xffff0000, v38
	v_lshlrev_b64 v[40:41], 12, v[34:35]
	v_lshlrev_b64 v[34:35], 11, v[38:39]
	v_lshl_add_u64 v[34:35], s[0:1], 0, v[34:35]
	v_lshl_add_u64 v[42:43], v[34:35], 0, v[142:143]
	v_cmp_gt_i32_e32 vcc, s16, v38
	s_waitcnt vmcnt(27)
	v_lshlrev_b32_e32 v44, 16, v224
	v_and_b32_e32 v45, 0xffff0000, v224
	v_lshlrev_b32_e32 v34, 16, v225
	v_and_b32_e32 v35, 0xffff0000, v225
	v_pk_add_f32 v[32:33], v[32:33], v[34:35]
	v_lshlrev_b32_e32 v34, 16, v226
	v_and_b32_e32 v35, 0xffff0000, v226
	v_pk_add_f32 v[26:27], v[26:27], v[34:35]
	v_lshlrev_b32_e32 v34, 16, v227
	v_and_b32_e32 v35, 0xffff0000, v227
	v_pk_add_f32 v[28:29], v[28:29], v[34:35]
	v_lshlrev_b64 v[34:35], 12, v[38:39]
	v_lshl_add_u64 v[34:35], s[74:75], 0, v[34:35]
	v_lshl_add_u64 v[36:37], s[4:5], 0, v[40:41]
	v_cndmask_b32_e32 v35, v37, v35, vcc
	v_cndmask_b32_e32 v34, v36, v34, vcc
	v_pk_add_f32 v[30:31], v[30:31], v[44:45]
	v_lshl_add_u64 v[34:35], v[34:35], 0, v[122:123]
	global_store_dwordx4 v[34:35], v[30:33], off nt
	global_store_dwordx4 v[34:35], v[26:29], off offset:16 nt
	s_waitcnt vmcnt(28)
	v_lshlrev_b32_e32 v30, 16, v231
	v_and_b32_e32 v31, 0xffff0000, v231
	v_pk_add_f32 v[24:25], v[24:25], v[30:31]
	v_lshlrev_b32_e32 v30, 16, v230
	v_and_b32_e32 v31, 0xffff0000, v230
	v_lshlrev_b32_e32 v28, 16, v229
	v_and_b32_e32 v29, 0xffff0000, v229
	v_pk_add_f32 v[20:21], v[20:21], v[28:29]
	v_lshlrev_b32_e32 v28, 16, v228
	v_and_b32_e32 v29, 0xffff0000, v228
	v_pk_add_f32 v[22:23], v[22:23], v[30:31]
	v_pk_add_f32 v[18:19], v[18:19], v[28:29]
	global_store_dwordx4 v[34:35], v[18:21], off offset:512 nt
	global_store_dwordx4 v[34:35], v[22:25], off offset:528 nt
	s_nop 0
	v_mov_b32_e32 v19, v0
	v_add_u32_e32 v22, s62, v147
	v_ashrrev_i32_e32 v23, 31, v22
	v_add_u32_e32 v18, 0xffff0000, v22
	v_lshlrev_b64 v[24:25], 12, v[18:19]
	v_lshlrev_b64 v[18:19], 11, v[22:23]
	v_lshl_add_u64 v[18:19], s[0:1], 0, v[18:19]
	v_lshl_add_u64 v[26:27], v[18:19], 0, v[142:143]
	v_cmp_gt_i32_e32 vcc, s16, v22
	s_mov_b64 s[0:1], s[10:11]
	s_waitcnt vmcnt(29)
	v_lshlrev_b32_e32 v28, 16, v232
	v_and_b32_e32 v29, 0xffff0000, v232
	v_lshlrev_b32_e32 v18, 16, v233
	v_and_b32_e32 v19, 0xffff0000, v233
	v_pk_add_f32 v[16:17], v[16:17], v[18:19]
	v_lshlrev_b32_e32 v18, 16, v234
	v_and_b32_e32 v19, 0xffff0000, v234
	v_pk_add_f32 v[10:11], v[10:11], v[18:19]
	v_lshlrev_b32_e32 v18, 16, v235
	v_and_b32_e32 v19, 0xffff0000, v235
	v_pk_add_f32 v[12:13], v[12:13], v[18:19]
	v_lshlrev_b64 v[18:19], 12, v[22:23]
	v_lshl_add_u64 v[18:19], s[74:75], 0, v[18:19]
	v_lshl_add_u64 v[20:21], s[4:5], 0, v[24:25]
	v_cndmask_b32_e32 v19, v21, v19, vcc
	v_cndmask_b32_e32 v18, v20, v18, vcc
	v_pk_add_f32 v[14:15], v[14:15], v[28:29]
	v_lshl_add_u64 v[18:19], v[18:19], 0, v[122:123]
	global_store_dwordx4 v[18:19], v[14:17], off nt
	global_store_dwordx4 v[18:19], v[10:13], off offset:16 nt
	s_and_b64 vcc, exec, s[8:9]
	s_mov_b64 s[4:5], s[12:13]
	s_waitcnt vmcnt(30)
	v_lshlrev_b32_e32 v14, 16, v239
	v_and_b32_e32 v15, 0xffff0000, v239
	v_pk_add_f32 v[4:5], v[4:5], v[14:15]
	v_lshlrev_b32_e32 v14, 16, v238
	v_and_b32_e32 v15, 0xffff0000, v238
	v_lshlrev_b32_e32 v12, 16, v237
	v_and_b32_e32 v13, 0xffff0000, v237
	v_pk_add_f32 v[8:9], v[8:9], v[12:13]
	v_lshlrev_b32_e32 v12, 16, v236
	v_and_b32_e32 v13, 0xffff0000, v236
	v_pk_add_f32 v[6:7], v[6:7], v[12:13]
	v_pk_add_f32 v[2:3], v[2:3], v[14:15]
	global_store_dwordx4 v[18:19], v[6:9], off offset:512 nt
	global_store_dwordx4 v[18:19], v[2:5], off offset:528 nt
	s_cbranch_vccz .LBB0_242
	s_waitcnt vmcnt(0)
	s_cmpk_gt_u32 s18, 0xff
	s_cbranch_scc1 .LBB0_257
	s_barrier
